# static s_setprio 1 for waves 4-7 at kernel entry
# speedup vs baseline: 1.0565x; 1.0071x over previous
; #define LAS __attribute__((address_space(3)))
; DEV unsigned xb_add(unsigned* p, unsigned v) { return __hip_atomic_fetch_add(p, v, __ATOMIC_RELAXED, __HIP_MEMORY_SCOPE_AGENT); }
; DEV unsigned xb_xcc_id() { return (unsigned)__builtin_amdgcn_s_getreg((3 << 11) | 20) & 0xFu; }
; __global__ void __launch_bounds__(512) mega_kernel(Params p, int ph_begin, int ph_end) {
;   extern __shared__ __attribute__((aligned(16))) char smem[];
;   volatile LAS unsigned* st = (volatile LAS unsigned*)(smem + SMEM_BYTES);
;   unsigned* bar = (unsigned*)(p.ws + OFF_BAR);
;   if (threadIdx.x < 2) st[threadIdx.x] = 0u;
;   __syncthreads();
;   const unsigned xcc = xb_xcc_id();
;   if (threadIdx.x == 0) (void)xb_add(&bar[XB_XCNT(xcc)], 1u);
_Z11mega_kernel6Paramsii:
	s_load_dwordx8 s[4:11], s[0:1], 0xc0
	v_and_b32_e32 v147, 0x3ff, v0
	v_writelane_b32 v242, s2, 0
	v_cmp_gt_u32_e32 vcc, 2, v147
	v_readfirstlane_b32 s3, v0
	s_bitcmp1_b32 s3, 8
	s_cbranch_scc0 .Lprio_skip
	s_setprio 1
.Lprio_skip:
	s_waitcnt lgkmcnt(0)
	v_writelane_b32 v242, s4, 1
	s_nop 1
	v_writelane_b32 v242, s5, 2
	v_writelane_b32 v242, s6, 3
	v_writelane_b32 v242, s7, 4
	v_writelane_b32 v242, s8, 5
	v_writelane_b32 v242, s9, 6
	v_writelane_b32 v242, s10, 7
	v_writelane_b32 v242, s11, 8
	s_and_saveexec_b64 s[2:3], vcc
	v_lshl_add_u32 v1, v147, 2, 0
	v_add_u32_e32 v1, 0x24000, v1
	v_mov_b32_e32 v2, 0
	ds_write_b32 v1, v2
	s_or_b64 exec, exec, s[2:3]
	s_load_dwordx8 s[4:11], s[0:1], 0xc0
	s_waitcnt lgkmcnt(0)
	s_barrier
	s_getreg_b32 s4, hwreg(HW_REG_XCC_ID, 0, 4)
	s_add_u32 s2, s10, 0x1f656100
	s_addc_u32 s3, s11, 0
	s_and_b32 s8, s4, 15
	v_cmp_eq_u32_e64 s[6:7], 0, v147
	s_mov_b64 s[4:5], exec
	s_nop 0
	v_writelane_b32 v242, s6, 9
	s_nop 1
	v_writelane_b32 v242, s7, 10
	s_and_b64 s[6:7], s[4:5], s[6:7]
	s_mov_b64 exec, s[6:7]
	s_cbranch_execz .LBB0_5
	s_mov_b64 s[6:7], exec
	v_mbcnt_lo_u32_b32 v1, s6, 0
	v_mbcnt_hi_u32_b32 v1, s7, v1
	v_cmp_eq_u32_e32 vcc, 0, v1
	s_and_b64 s[10:11], exec, vcc
	s_mov_b64 exec, s[10:11]
	s_cbranch_execz .LBB0_5
	s_lshl_b32 s9, s8, 8
	s_bcnt1_i32_b64 s6, s[6:7]
	v_mov_b32_e32 v1, s9
	v_mov_b32_e32 v2, s6
	global_atomic_add v1, v2, s[2:3] offset:1024
